# GEMM K-loop heads aligned to 64 bytes (in-proj, out-proj, PEER query), later phases kept at their original 8-byte code phase
# baseline (speedup 1.0000x reference)
;     __device__ __forceinline__ bool next(int i, Unit& o) const { if (i != 0) return false; o = u; return true; }
; template <class Epi, class Sched, bool ALIGN_EPI = false, bool SP2 = false>
; __device__ __forceinline__ void gemm_phase(PG8_LAS unsigned char* lds, const Gemm g, const Sched& S, const Epi& E, int wid  ) {
;     ...
;     for (;;) {
;         const bool has_next = S.next(ui + 1, nxt);
;         const char* nA = has_next ? (const char*)g.A + (size_t)nxt.pm * tstep : cA; const char* nB = has_next ? (const char*)g.Bt + (size_t)nxt.pn * tstep : cB;
;         for (int t = 0; t < nt; t += 2) {
;             const bool last = (t == nt - 2);
;             const char* a1 = cA + (size_t)(t + 1) * kstep;
;             const char* a2 = last ? nA : cA + (size_t)(t + 2) * kstep; const char* b2 = last ? nB : cB + (size_t)(t + 2) * kstep;
;     ...
; #pragma unroll
;         for (int a = 0; a < 2; ++a)
; #pragma unroll
;             for (int b = 0; b < 2; ++b)
; #pragma unroll
;                 for (int m = 0; m < 4; ++m)
; #pragma unroll
;                     for (int n = 0; n < 2; ++n) acc[a][b][m][n] = (acc_t){0, 0, 0, 0};
.LBB0_154:
	s_ashr_i32 s13, s12, 31
	s_lshl_b64 s[14:15], s[12:13], 19
	v_readlane_b32 s16, v254, 25
	v_readlane_b32 s17, v254, 26
	s_add_u32 s14, s16, s14
	s_addc_u32 s15, s17, s15
	s_and_b64 s[16:17], s[4:5], exec
	s_cselect_b32 s13, s15, s21
	s_cselect_b32 s38, s14, s20
	s_ashr_i32 s3, s2, 31
	s_lshl_b64 s[16:17], s[2:3], 19
	s_add_u32 s16, s6, s16
	s_addc_u32 s17, s7, s17
	s_and_b64 s[24:25], s[4:5], exec
	s_cselect_b32 s3, s17, s23
	s_cselect_b32 s39, s16, s22
	s_add_u32 s20, s20, 0x40080
	s_addc_u32 s21, s21, 0
	s_add_u32 s40, s22, 0x100
	v_mov_b32_e32 v0, 0
	s_addc_u32 s41, s23, 0
	s_mov_b32 s42, -2
	v_mov_b32_e32 v1, v0
	v_mov_b32_e32 v2, v0
	v_mov_b32_e32 v3, v0
	v_mov_b32_e32 v4, v0
	v_mov_b32_e32 v5, v0
	v_mov_b32_e32 v6, v0
	v_mov_b32_e32 v7, v0
	v_mov_b32_e32 v16, v0
	v_mov_b32_e32 v17, v0
	v_mov_b32_e32 v18, v0
	v_mov_b32_e32 v19, v0
	v_mov_b32_e32 v20, v0
	v_mov_b32_e32 v21, v0
	v_mov_b32_e32 v22, v0
	v_mov_b32_e32 v23, v0
	v_mov_b32_e32 v32, v0
	v_mov_b32_e32 v33, v0
	v_mov_b32_e32 v34, v0
	v_mov_b32_e32 v35, v0
	v_mov_b32_e32 v36, v0
	v_mov_b32_e32 v37, v0
	v_mov_b32_e32 v38, v0
	v_mov_b32_e32 v39, v0
	v_mov_b32_e32 v48, v0
	v_mov_b32_e32 v49, v0
	v_mov_b32_e32 v50, v0
	v_mov_b32_e32 v51, v0
	v_mov_b32_e32 v52, v0
	v_mov_b32_e32 v53, v0
	v_mov_b32_e32 v54, v0
	v_mov_b32_e32 v55, v0
	v_mov_b32_e32 v8, v0
	v_mov_b32_e32 v9, v0
	v_mov_b32_e32 v10, v0
	v_mov_b32_e32 v11, v0
	v_mov_b32_e32 v12, v0
	v_mov_b32_e32 v13, v0
	v_mov_b32_e32 v14, v0
	v_mov_b32_e32 v15, v0
	v_mov_b32_e32 v24, v0
	v_mov_b32_e32 v25, v0
	v_mov_b32_e32 v26, v0
	v_mov_b32_e32 v27, v0
	v_mov_b32_e32 v28, v0
	v_mov_b32_e32 v29, v0
	v_mov_b32_e32 v30, v0
	v_mov_b32_e32 v31, v0
	v_mov_b32_e32 v40, v0
	v_mov_b32_e32 v41, v0
	v_mov_b32_e32 v42, v0
	v_mov_b32_e32 v43, v0
	v_mov_b32_e32 v44, v0
	v_mov_b32_e32 v45, v0
	v_mov_b32_e32 v46, v0
	v_mov_b32_e32 v47, v0
	v_mov_b32_e32 v56, v0
	v_mov_b32_e32 v57, v0
	v_mov_b32_e32 v58, v0
	v_mov_b32_e32 v59, v0
	v_mov_b32_e32 v60, v0
	v_mov_b32_e32 v61, v0
	v_mov_b32_e32 v62, v0
	v_mov_b32_e32 v63, v0
	v_mov_b32_e32 v64, v0
	v_mov_b32_e32 v65, v0
	v_mov_b32_e32 v66, v0
	v_mov_b32_e32 v67, v0
	v_mov_b32_e32 v68, v0
	v_mov_b32_e32 v69, v0
	v_mov_b32_e32 v70, v0
	v_mov_b32_e32 v71, v0
	v_mov_b32_e32 v80, v0
	v_mov_b32_e32 v81, v0
	v_mov_b32_e32 v82, v0
	v_mov_b32_e32 v83, v0
	v_mov_b32_e32 v84, v0
	v_mov_b32_e32 v85, v0
	v_mov_b32_e32 v86, v0
	v_mov_b32_e32 v87, v0
	v_mov_b32_e32 v96, v0
	v_mov_b32_e32 v97, v0
	v_mov_b32_e32 v98, v0
	v_mov_b32_e32 v99, v0
	v_mov_b32_e32 v100, v0
	v_mov_b32_e32 v101, v0
	v_mov_b32_e32 v102, v0
	v_mov_b32_e32 v103, v0
	v_mov_b32_e32 v124, v0
	v_mov_b32_e32 v125, v0
	v_mov_b32_e32 v126, v0
	v_mov_b32_e32 v127, v0
	v_mov_b32_e32 v132, v0
	v_mov_b32_e32 v133, v0
	v_mov_b32_e32 v134, v0
	v_mov_b32_e32 v135, v0
	v_mov_b32_e32 v72, v0
	v_mov_b32_e32 v73, v0
	v_mov_b32_e32 v74, v0
	v_mov_b32_e32 v75, v0
	v_mov_b32_e32 v76, v0
	v_mov_b32_e32 v77, v0
	v_mov_b32_e32 v78, v0
	v_mov_b32_e32 v79, v0
	v_mov_b32_e32 v88, v0
	v_mov_b32_e32 v89, v0
	v_mov_b32_e32 v90, v0
	v_mov_b32_e32 v91, v0
	v_mov_b32_e32 v92, v0
	v_mov_b32_e32 v93, v0
	v_mov_b32_e32 v94, v0
	v_mov_b32_e32 v95, v0
	v_mov_b32_e32 v104, v0
	v_mov_b32_e32 v105, v0
	v_mov_b32_e32 v106, v0
	v_mov_b32_e32 v107, v0
	v_mov_b32_e32 v116, v0
	v_mov_b32_e32 v117, v0
	v_mov_b32_e32 v118, v0
	v_mov_b32_e32 v119, v0
	v_mov_b32_e32 v136, v0
	v_mov_b32_e32 v137, v0
	v_mov_b32_e32 v138, v0
	v_mov_b32_e32 v139, v0
	v_mov_b32_e32 v140, v0
	v_mov_b32_e32 v141, v0
	v_mov_b32_e32 v142, v0
	v_mov_b32_e32 v143, v0
	.p2align 6

;     __device__ __forceinline__ bool next(int i, Unit& o) const { if (i != 0) return false; o = u; return true; }
; template <class Epi, class Sched, bool ALIGN_EPI = false, bool SP2 = false>
; __device__ __forceinline__ void gemm_phase(PG8_LAS unsigned char* lds, const Gemm g, const Sched& S, const Epi& E, int wid  ) {
;     ...
;     for (;;) {
;         const bool has_next = S.next(ui + 1, nxt);
;         const char* nA = has_next ? (const char*)g.A + (size_t)nxt.pm * tstep : cA; const char* nB = has_next ? (const char*)g.Bt + (size_t)nxt.pn * tstep : cB;
;         for (int t = 0; t < nt; t += 2) {
;             const bool last = (t == nt - 2);
;             const char* a1 = cA + (size_t)(t + 1) * kstep;
;             const char* a2 = last ? nA : cA + (size_t)(t + 2) * kstep; const char* b2 = last ? nB : cB + (size_t)(t + 2) * kstep;
;     ...
; #pragma unroll
;         for (int a = 0; a < 2; ++a)
; #pragma unroll
;             for (int b = 0; b < 2; ++b)
; #pragma unroll
;                 for (int m = 0; m < 4; ++m)
; #pragma unroll
;                     for (int n = 0; n < 2; ++n) acc[a][b][m][n] = (acc_t){0, 0, 0, 0};
.LBB0_509:
	s_ashr_i32 s21, s20, 31
	s_lshl_b64 s[22:23], s[20:21], 20
	s_add_u32 s22, s82, s22
	s_addc_u32 s23, s83, s23
	s_and_b64 s[24:25], s[6:7], exec
	s_cselect_b32 s3, s23, s27
	s_cselect_b32 s21, s22, s26
	s_ashr_i32 s19, s18, 31
	s_lshl_b64 s[24:25], s[18:19], 20
	s_add_u32 s24, s37, s24
	s_addc_u32 s25, s38, s25
	s_and_b64 s[30:31], s[6:7], exec
	s_cselect_b32 s19, s25, s29
	s_cselect_b32 s52, s24, s28
	s_add_u32 s26, s26, 0x80080
	s_addc_u32 s27, s27, 0
	s_add_u32 s53, s28, 0x100
	v_mov_b32_e32 v0, 0
	s_addc_u32 s54, s29, 0
	s_mov_b32 s55, -2
	s_waitcnt lgkmcnt(0)
	v_mov_b32_e32 v1, v0
	v_mov_b32_e32 v2, v0
	v_mov_b32_e32 v3, v0
	v_mov_b32_e32 v4, v0
	v_mov_b32_e32 v5, v0
	v_mov_b32_e32 v6, v0
	v_mov_b32_e32 v7, v0
	v_mov_b32_e32 v16, v0
	v_mov_b32_e32 v17, v0
	v_mov_b32_e32 v18, v0
	v_mov_b32_e32 v19, v0
	v_mov_b32_e32 v20, v0
	v_mov_b32_e32 v21, v0
	v_mov_b32_e32 v22, v0
	v_mov_b32_e32 v23, v0
	v_mov_b32_e32 v32, v0
	v_mov_b32_e32 v33, v0
	v_mov_b32_e32 v34, v0
	v_mov_b32_e32 v35, v0
	v_mov_b32_e32 v36, v0
	v_mov_b32_e32 v37, v0
	v_mov_b32_e32 v38, v0
	v_mov_b32_e32 v39, v0
	v_mov_b32_e32 v48, v0
	v_mov_b32_e32 v49, v0
	v_mov_b32_e32 v50, v0
	v_mov_b32_e32 v51, v0
	v_mov_b32_e32 v52, v0
	v_mov_b32_e32 v53, v0
	v_mov_b32_e32 v54, v0
	v_mov_b32_e32 v55, v0
	v_mov_b32_e32 v8, v0
	v_mov_b32_e32 v9, v0
	v_mov_b32_e32 v10, v0
	v_mov_b32_e32 v11, v0
	v_mov_b32_e32 v12, v0
	v_mov_b32_e32 v13, v0
	v_mov_b32_e32 v14, v0
	v_mov_b32_e32 v15, v0
	v_mov_b32_e32 v24, v0
	v_mov_b32_e32 v25, v0
	v_mov_b32_e32 v26, v0
	v_mov_b32_e32 v27, v0
	v_mov_b32_e32 v28, v0
	v_mov_b32_e32 v29, v0
	v_mov_b32_e32 v30, v0
	v_mov_b32_e32 v31, v0
	v_mov_b32_e32 v40, v0
	v_mov_b32_e32 v41, v0
	v_mov_b32_e32 v42, v0
	v_mov_b32_e32 v43, v0
	v_mov_b32_e32 v44, v0
	v_mov_b32_e32 v45, v0
	v_mov_b32_e32 v46, v0
	v_mov_b32_e32 v47, v0
	v_mov_b32_e32 v56, v0
	v_mov_b32_e32 v57, v0
	v_mov_b32_e32 v58, v0
	v_mov_b32_e32 v59, v0
	v_mov_b32_e32 v60, v0
	v_mov_b32_e32 v61, v0
	v_mov_b32_e32 v62, v0
	v_mov_b32_e32 v63, v0
	v_mov_b32_e32 v64, v0
	v_mov_b32_e32 v65, v0
	v_mov_b32_e32 v66, v0
	v_mov_b32_e32 v67, v0
	v_mov_b32_e32 v68, v0
	v_mov_b32_e32 v69, v0
	v_mov_b32_e32 v70, v0
	v_mov_b32_e32 v71, v0
	v_mov_b32_e32 v80, v0
	v_mov_b32_e32 v81, v0
	v_mov_b32_e32 v82, v0
	v_mov_b32_e32 v83, v0
	v_mov_b32_e32 v84, v0
	v_mov_b32_e32 v85, v0
	v_mov_b32_e32 v86, v0
	v_mov_b32_e32 v87, v0
	v_mov_b32_e32 v96, v0
	v_mov_b32_e32 v97, v0
	v_mov_b32_e32 v98, v0
	v_mov_b32_e32 v99, v0
	v_mov_b32_e32 v100, v0
	v_mov_b32_e32 v101, v0
	v_mov_b32_e32 v102, v0
	v_mov_b32_e32 v103, v0
	v_mov_b32_e32 v112, v0
	v_mov_b32_e32 v113, v0
	v_mov_b32_e32 v114, v0
	v_mov_b32_e32 v115, v0
	v_mov_b32_e32 v116, v0
	v_mov_b32_e32 v117, v0
	v_mov_b32_e32 v118, v0
	v_mov_b32_e32 v119, v0
	v_mov_b32_e32 v72, v0
	v_mov_b32_e32 v73, v0
	v_mov_b32_e32 v74, v0
	v_mov_b32_e32 v75, v0
	v_mov_b32_e32 v76, v0
	v_mov_b32_e32 v77, v0
	v_mov_b32_e32 v78, v0
	v_mov_b32_e32 v79, v0
	v_mov_b32_e32 v88, v0
	v_mov_b32_e32 v89, v0
	v_mov_b32_e32 v90, v0
	v_mov_b32_e32 v91, v0
	v_mov_b32_e32 v92, v0
	v_mov_b32_e32 v93, v0
	v_mov_b32_e32 v94, v0
	v_mov_b32_e32 v95, v0
	v_mov_b32_e32 v104, v0
	v_mov_b32_e32 v105, v0
	v_mov_b32_e32 v106, v0
	v_mov_b32_e32 v107, v0
	v_mov_b32_e32 v108, v0
	v_mov_b32_e32 v109, v0
	v_mov_b32_e32 v110, v0
	v_mov_b32_e32 v111, v0
	v_mov_b32_e32 v120, v0
	v_mov_b32_e32 v121, v0
	v_mov_b32_e32 v122, v0
	v_mov_b32_e32 v123, v0
	v_mov_b32_e32 v124, v0
	v_mov_b32_e32 v125, v0
	v_mov_b32_e32 v126, v0
	v_mov_b32_e32 v127, v0
	s_waitcnt vmcnt(0)
	.p2align 6

; __device__ __forceinline__ int fresh_lane() { int l; asm volatile("v_mbcnt_lo_u32_b32 %0, -1, 0\n\tv_mbcnt_hi_u32_b32 %0, -1, %0" : "=v"(l)); return l; }
; #define PG8_STAGE(bufoff, gbase, voff) do { _Pragma("unroll") for (int _i = 0; _i < 2; ++_i) \
;         __builtin_amdgcn_global_load_lds((const unsigned*)((const char*)(gbase) + (voff)[_i]), (PG8_LAS unsigned*)(lds + (bufoff) + ldsw + _i * 8192), 16, 0, 0); } while (0)
; #define PG8_WAIT_V(n) asm volatile("s_waitcnt vmcnt(" #n ")" ::: "memory")
; #define PG8_BAR __builtin_amdgcn_s_barrier()
; template <class Epi, class Sched, bool ALIGN_EPI = false, bool SP2 = false>
; __device__ __forceinline__ void gemm_phase(PG8_LAS unsigned char* lds, const Gemm g, const Sched& S, const Epi& E, int wid  ) {
;     const int lane = fresh_lane(), tid = wid * 64 + lane, wr = wid >> 2, wc = wid & 3, fr = lane & 15, fq = lane >> 4;
;     const int K = g.K, nt = K / BK;
;     unsigned voffA[2], voffB[2];
; #pragma unroll
;     for (int i = 0; i < 2; ++i) { int R, C; stage_rc(tid * 16 + i * 8192, R, C); const int Rb = Epi::PERM ? ((R & ~31) + perm32(R & 31)) : R;
;         voffA[i] = (unsigned)(R * K + C) * 2u; voffB[i] = (unsigned)(Rb * K + C) * 2u; }
;     const size_t kstep = (size_t)(BK * 2);
;     const size_t hstep = (size_t)HALF * K * 2;
;     const size_t tstep = 2 * hstep;
;     const unsigned ldsw = (unsigned)wid * 1024u;
;     const int aoff = lds_byte(wr * 64 + fr, fq * 8), boff = lds_byte(wc * 32 + fr, fq * 8);
;     ...
;     if constexpr (SP2) {
;         PG8_STAGE(PG8_SB(0, 0), cB, voffB); PG8_STAGE(PG8_SB(0, 1), cB + hstep, voffB); PG8_STAGE(PG8_SA(0, 0), cA, voffA); PG8_STAGE(PG8_SA(0, 1), cA + hstep, voffA);
;         if (wr == 1) PG8_BAR;
;         PG8_WAIT_V(2); PG8_BAR;
;         PG8_STAGE(PG8_SB(1, 0), cB + kstep, voffB); PG8_STAGE(PG8_SA(1, 0), cA + kstep, voffA); PG8_STAGE(PG8_SB(1, 1), cB + hstep + kstep, voffB);
;         PG8_WAIT_V(6); PG8_BAR;
.LBB0_594:
	v_lshl_add_u64 v[6:7], v[6:7], 0, s[18:19]
	s_add_i32 m0, s27, 0x18000
	s_waitcnt vmcnt(2)
	s_barrier
	global_load_lds_dwordx4 v[6:7], off
	v_lshl_add_u64 v[4:5], v[4:5], 0, s[18:19]
	s_add_i32 m0, s27, 0x1a000
	s_add_i32 s56, s27, 0x8000
	s_add_i32 s57, s27, 0xa000
	global_load_lds_dwordx4 v[4:5], off
	v_lshl_add_u64 v[2:3], v[2:3], 0, s[18:19]
	s_mov_b32 m0, s56
	s_add_u32 s24, s0, 0x40080
	global_load_lds_dwordx4 v[2:3], off
	v_lshl_add_u64 v[0:1], v[0:1], 0, s[18:19]
	s_mov_b32 m0, s57
	s_addc_u32 s25, s1, 0
	global_load_lds_dwordx4 v[0:1], off
	v_lshl_add_u64 v[0:1], s[24:25], 0, v[148:149]
	s_add_i32 m0, s27, 0x1c000
	v_and_b32_e32 v170, 15, v169
	global_load_lds_dwordx4 v[0:1], off
	v_lshl_add_u64 v[0:1], s[24:25], 0, v[132:133]
	s_add_i32 m0, s27, 0x1e000
	s_add_u32 s22, s29, s22
	global_load_lds_dwordx4 v[0:1], off
	v_lshlrev_b32_e32 v0, 14, v8
	v_and_b32_e32 v0, 0xffff8000, v0
	v_lshl_add_u32 v0, v9, 11, v0
	v_and_b32_e32 v1, 1, v8
	v_lshl_or_b32 v0, v1, 6, v0
	v_lshl_add_u32 v0, v10, 1, v0
	v_mov_b32_e32 v1, v149
	s_addc_u32 s23, s30, s23
	v_lshl_add_u64 v[134:135], s[22:23], 0, v[0:1]
	v_lshlrev_b32_e32 v0, 14, v11
	v_and_b32_e32 v0, 0xffff8000, v0
	v_or_b32_e32 v171, s71, v170
	v_lshl_add_u32 v0, v12, 11, v0
	v_and_b32_e32 v1, 1, v11
	v_lshlrev_b32_e32 v15, 6, v171
	v_and_b32_e32 v16, 48, v169
	v_and_b32_e32 v14, 0xfffffc00, v14
	v_lshlrev_b32_e32 v17, 2, v171
	v_lshl_or_b32 v0, v1, 6, v0
	v_and_or_b32 v15, v15, s48, v16
	v_and_b32_e32 v17, 32, v17
	v_add_u32_e32 v18, s35, v14
	v_lshlrev_b32_e32 v19, 2, v169
	v_add_u32_e32 v14, s76, v14
	s_waitcnt vmcnt(6)
	v_lshl_add_u32 v0, v13, 1, v0
	v_mov_b32_e32 v1, v149
	v_lshl_or_b32 v16, v170, 6, v16
	v_and_b32_e32 v19, 32, v19
	v_bitop3_b32 v14, v15, v14, v17 bitop3:0xde
	v_lshl_add_u64 v[136:137], s[22:23], 0, v[0:1]
	s_add_u32 s58, s31, s4
	v_mov_b32_e32 v0, 0
	v_bitop3_b32 v138, v16, v18, v19 bitop3:0xde
	s_addc_u32 s59, s36, s5
	s_mov_b32 s60, -2
	s_mov_b64 s[4:5], 0
	v_add_u32_e32 v139, 0, v14
	v_mov_b32_e32 v1, v0
	v_mov_b32_e32 v2, v0
	v_mov_b32_e32 v3, v0
	v_mov_b32_e32 v4, v0
	v_mov_b32_e32 v5, v0
	v_mov_b32_e32 v6, v0
	v_mov_b32_e32 v7, v0
	v_mov_b32_e32 v12, v0
	v_mov_b32_e32 v13, v0
	v_mov_b32_e32 v14, v0
	v_mov_b32_e32 v15, v0
	v_mov_b32_e32 v20, v0
	v_mov_b32_e32 v21, v0
	v_mov_b32_e32 v22, v0
	v_mov_b32_e32 v23, v0
	v_mov_b32_e32 v28, v0
	v_mov_b32_e32 v29, v0
	v_mov_b32_e32 v30, v0
	v_mov_b32_e32 v31, v0
	v_mov_b32_e32 v36, v0
	v_mov_b32_e32 v37, v0
	v_mov_b32_e32 v38, v0
	v_mov_b32_e32 v39, v0
	v_mov_b32_e32 v44, v0
	v_mov_b32_e32 v45, v0
	v_mov_b32_e32 v46, v0
	v_mov_b32_e32 v47, v0
	v_mov_b32_e32 v52, v0
	v_mov_b32_e32 v53, v0
	v_mov_b32_e32 v54, v0
	v_mov_b32_e32 v55, v0
	v_mov_b32_e32 v8, v0
	v_mov_b32_e32 v9, v0
	v_mov_b32_e32 v10, v0
	v_mov_b32_e32 v11, v0
	v_mov_b32_e32 v16, v0
	v_mov_b32_e32 v17, v0
	v_mov_b32_e32 v18, v0
	v_mov_b32_e32 v19, v0
	v_mov_b32_e32 v24, v0
	v_mov_b32_e32 v25, v0
	v_mov_b32_e32 v26, v0
	v_mov_b32_e32 v27, v0
	v_mov_b32_e32 v32, v0
	v_mov_b32_e32 v33, v0
	v_mov_b32_e32 v34, v0
	v_mov_b32_e32 v35, v0
	v_mov_b32_e32 v40, v0
	v_mov_b32_e32 v41, v0
	v_mov_b32_e32 v42, v0
	v_mov_b32_e32 v43, v0
	v_mov_b32_e32 v48, v0
	v_mov_b32_e32 v49, v0
	v_mov_b32_e32 v50, v0
	v_mov_b32_e32 v51, v0
	v_mov_b32_e32 v56, v0
	v_mov_b32_e32 v57, v0
	v_mov_b32_e32 v58, v0
	v_mov_b32_e32 v59, v0
	v_mov_b32_e32 v60, v0
	v_mov_b32_e32 v61, v0
	v_mov_b32_e32 v62, v0
	v_mov_b32_e32 v63, v0
	v_mov_b32_e32 v64, v0
	v_mov_b32_e32 v65, v0
	v_mov_b32_e32 v66, v0
	v_mov_b32_e32 v67, v0
	v_mov_b32_e32 v68, v0
	v_mov_b32_e32 v69, v0
	v_mov_b32_e32 v70, v0
	v_mov_b32_e32 v71, v0
	v_mov_b32_e32 v80, v0
	v_mov_b32_e32 v81, v0
	v_mov_b32_e32 v82, v0
	v_mov_b32_e32 v83, v0
	v_mov_b32_e32 v84, v0
	v_mov_b32_e32 v85, v0
	v_mov_b32_e32 v86, v0
	v_mov_b32_e32 v87, v0
	v_mov_b32_e32 v96, v0
	v_mov_b32_e32 v97, v0
	v_mov_b32_e32 v98, v0
	v_mov_b32_e32 v99, v0
	v_mov_b32_e32 v100, v0
	v_mov_b32_e32 v101, v0
	v_mov_b32_e32 v102, v0
	v_mov_b32_e32 v103, v0
	v_mov_b32_e32 v112, v0
	v_mov_b32_e32 v113, v0
	v_mov_b32_e32 v114, v0
	v_mov_b32_e32 v115, v0
	v_mov_b32_e32 v116, v0
	v_mov_b32_e32 v117, v0
	v_mov_b32_e32 v118, v0
	v_mov_b32_e32 v119, v0
	v_mov_b32_e32 v72, v0
	v_mov_b32_e32 v73, v0
	v_mov_b32_e32 v74, v0
	v_mov_b32_e32 v75, v0
	v_mov_b32_e32 v76, v0
	v_mov_b32_e32 v77, v0
	v_mov_b32_e32 v78, v0
	v_mov_b32_e32 v79, v0
	v_mov_b32_e32 v88, v0
	v_mov_b32_e32 v89, v0
	v_mov_b32_e32 v90, v0
	v_mov_b32_e32 v91, v0
	v_mov_b32_e32 v92, v0
	v_mov_b32_e32 v93, v0
	v_mov_b32_e32 v94, v0
	v_mov_b32_e32 v95, v0
	v_mov_b32_e32 v104, v0
	v_mov_b32_e32 v105, v0
	v_mov_b32_e32 v106, v0
	v_mov_b32_e32 v107, v0
	v_mov_b32_e32 v108, v0
	v_mov_b32_e32 v109, v0
	v_mov_b32_e32 v110, v0
	v_mov_b32_e32 v111, v0
	v_mov_b32_e32 v120, v0
	v_mov_b32_e32 v121, v0
	v_mov_b32_e32 v122, v0
	v_mov_b32_e32 v123, v0
	v_mov_b32_e32 v124, v0
	v_mov_b32_e32 v125, v0
	v_mov_b32_e32 v126, v0
	v_mov_b32_e32 v127, v0
	s_barrier
	s_waitcnt vmcnt(0)
	.p2align 6

; __device__ __forceinline__ int fresh_lane() { int l; asm volatile("v_mbcnt_lo_u32_b32 %0, -1, 0\n\tv_mbcnt_hi_u32_b32 %0, -1, %0" : "=v"(l)); return l; }
; #define LAS __attribute__((address_space(3)))
; __device__ __forceinline__ void p6a_hist(Frame& F) {
;     const int lane = fresh_lane(), tid = F.wave * 64 + lane;
;     LAS unsigned* cnt = (LAS unsigned*)F.lds;
;     unsigned* H = (unsigned*)(F.ws + WS_H); const float* SS = (const float*)(F.ws + WS_SS); float* RSTD2 = (float*)(F.ws + WS_RSTD2);
; #pragma unroll 1
;     for (int j = F.vcu; j < IG_NSUB; j += F.G) {
;         cnt[tid] = 0u; cnt[tid + 512] = 0u;
;         __syncthreads();
;         const v4u* re = (const v4u*)(F.ws + WS_RE16 + (size_t)j * IG_SUBT * 256);
; __global__ void __launch_bounds__(NTHREADS, 2) hymba_fwd(Args args) {
;     ...
;     const unsigned rank = MISC[10];
.LBB0_654:
	s_or_b64 exec, exec, s[0:1]
	s_add_i32 s0, 0, 0x20168
	s_waitcnt lgkmcnt(0)
	v_mov_b32_e32 v0, s0
	s_add_u32 s4, s74, 0x7600000
	s_barrier
	s_nop 0
	ds_read_b32 v0, v0
	s_addc_u32 s5, s75, 0
	s_add_u32 s38, s74, 0x7700000
	s_addc_u32 s39, s75, 0
	v_readlane_b32 s0, v254, 2
	s_cmpk_lt_i32 s0, 0x100
	s_cselect_b64 s[6:7], -1, 0
	s_waitcnt lgkmcnt(0)
	v_readfirstlane_b32 s33, v0
	s_and_b64 vcc, exec, s[6:7]
	v_mbcnt_lo_u32_b32 v0, -1, 0
	v_mbcnt_hi_u32_b32 v0, -1, v0
	s_cbranch_vccz .LBB0_659
	v_readlane_b32 s0, v254, 48
	v_readlane_b32 s19, v254, 2
	s_lshl_b32 s16, s68, 10
	v_add_u32_e32 v4, s0, v0
	s_movk_i32 s0, 0x60
	v_cmp_gt_i32_e64 s[2:3], s0, v4
	s_mul_i32 s0, s19, 0x60
	v_add_u32_e32 v2, s0, v4
	s_mul_i32 s0, s19, 0x6000
	s_mul_hi_i32 s1, s19, 0x6000
	s_add_u32 s0, s74, s0
	v_ashrrev_i32_e32 v5, 31, v4
	s_addc_u32 s1, s75, s1
	v_lshl_add_u32 v6, v4, 2, 0
	v_lshl_add_u32 v0, s19, 10, v4
	v_lshl_add_u64 v[4:5], v[4:5], 4, s[0:1]
	s_mov_b64 s[0:1], 0x1c800000
	s_mul_i32 s17, s68, 0x60
	v_lshl_add_u64 v[4:5], v[4:5], 0, s[0:1]
	s_mul_hi_i32 s9, s68, 0x6000
	s_mul_i32 s8, s68, 0x6000
	v_mov_b32_e32 v7, 0
	v_mov_b32_e32 v8, 1
	v_mov_b32_e32 v9, 0x358637bd
	s_mov_b32 s18, 0xf800000
	v_mov_b32_e32 v10, 0x260
	s_branch .LBB0_657
